# v010 + swiglu ALIGN_EPI barrier of waves 0-3 moved to after the first epilogue row-group
# baseline (speedup 1.0000x reference)
; __device__ __forceinline__ unsigned pk_bf16(float lo, float hi) { f32x2 v = {lo, hi}; bf16x2_t b = __builtin_convertvector(v, bf16x2_t); return __builtin_bit_cast(unsigned, b); }
; __device__ __forceinline__ float fast_exp2(float x) { return __builtin_amdgcn_exp2f(x); }
; __device__ __forceinline__ float fast_rcp(float x) { return __builtin_amdgcn_rcpf(x); }
; #define PG8_BAR __builtin_amdgcn_s_barrier()
;     __device__ __forceinline__ void operator()(const f32x4 (&acc)[2][2][4][2], const Unit& u, int wr, int wc, int fr, int fq, float rp0, float rp1, const f32x4& raw0, const f32x4& raw1, float& rn0, float& rn1) const {
;         const int row0 = u.pm * BM + wr * 64 + fr, col0 = u.pn * 128 + wc * 32 + 8 * fq;
;         float rs[8];
; #pragma unroll
;         for (int k = 0; k < 8; ++k) rs[k] = __shfl((k >> 2) ? rp1 : rp0, fr + 16 * (k & 3));
; #pragma unroll
;         for (int ai = 0; ai < 2; ++ai)
; #pragma unroll
;             for (int m = 0; m < 4; ++m) {
;                 const int row = row0 + ai * HALF + m * 16; const float r = rs[ai * 4 + m];
;                 const float c1 = -1.4426950408889634f * r, r2 = r * r;
;                 const f32x4 ga = acc[ai][0][m][0], gb = acc[ai][0][m][1];
;                 const f32x4 ta = ga * c1, tb = gb * c1;
;                 f32x4 ea, eb;
; #pragma unroll
;                 for (int j = 0; j < 4; ++j) { ea[j] = fast_exp2(ta[j]); eb[j] = fast_exp2(tb[j]); }
;                 const f32x4 da = ea + 1.f, db = eb + 1.f;
;                 f32x4 qa, qb;
; #pragma unroll
;                 for (int j = 0; j < 4; ++j) { qa[j] = fast_rcp(da[j]); qb[j] = fast_rcp(db[j]); }
;                 const f32x4 oa = ((ga * acc[ai][1][m][0]) * r2) * qa, ob = ((gb * acc[ai][1][m][1]) * r2) * qb;
;                 u32x4 w;
;                 w.x = pk_bf16(oa[0], oa[1]); w.y = pk_bf16(oa[2], oa[3]); w.z = pk_bf16(ob[0], ob[1]); w.w = pk_bf16(ob[2], ob[3]);
;                 if (ai == 0 && m == 0) rstd_finish(raw0, raw1, rn0, rn1);
;                 *(u32x4*)(O + (size_t)row * FF + col0) = w;
; template <class Epi>
; __device__ __forceinline__ void gemm_phase(LAS unsigned char* lds, const Gemm g, const Order& S, const Epi& E, const int tid) {
;     ...
;         if (wr == 0) PG8_BAR;
.LBB0_322:
	s_andn2_b64 vcc, exec, s[4:5]
	s_mov_b64 s[4:5], -1
	v_and_or_b32 v157, v197, 64, v154
	v_lshlrev_b32_e32 v157, 2, v157
	ds_bpermute_b32 v162, v157, v144
	ds_bpermute_b32 v163, v157, v144 offset:64
	ds_bpermute_b32 v164, v157, v144 offset:128
	ds_bpermute_b32 v165, v157, v144 offset:192
	ds_bpermute_b32 v166, v157, v145
	ds_bpermute_b32 v167, v157, v145 offset:64
	ds_bpermute_b32 v168, v157, v145 offset:128
	ds_bpermute_b32 v169, v157, v145 offset:192
	ds_bpermute_b32 v200, v157, v252
	ds_bpermute_b32 v202, v157, v252 offset:64
	ds_bpermute_b32 v204, v157, v252 offset:128
	ds_bpermute_b32 v206, v157, v252 offset:192
	ds_bpermute_b32 v220, v157, v253
	ds_bpermute_b32 v222, v157, v253 offset:64
	ds_bpermute_b32 v224, v157, v253 offset:128
	ds_bpermute_b32 v226, v157, v253 offset:192
	v_lshl_add_u32 v153, s6, 8, v155
	v_lshl_or_b32 v160, s7, 7, v151
	v_mul_u32_u24_e32 v161, 0x1600, v153
	v_lshl_add_u32 v161, v160, 1, v161
	s_waitcnt lgkmcnt(0)
	v_mul_f32_e32 v228, 0xbfb8aa3b, v162
	v_pk_mul_f32 v[126:127], v[118:119], v[126:127]
	v_pk_mul_f32 v[128:129], v[120:121], v[128:129]
	v_pk_mul_f32 v[122:123], v[114:115], v[122:123]
	v_pk_mul_f32 v[124:125], v[116:117], v[124:125]
	v_pk_mul_f32 v[118:119], v[118:119], v[228:229] op_sel_hi:[1,0]
	v_pk_mul_f32 v[120:121], v[120:121], v[228:229] op_sel_hi:[1,0]
	v_pk_mul_f32 v[114:115], v[114:115], v[228:229] op_sel_hi:[1,0]
	v_pk_mul_f32 v[116:117], v[116:117], v[228:229] op_sel_hi:[1,0]
	v_exp_f32_e32 v118, v118
	v_exp_f32_e32 v119, v119
	v_exp_f32_e32 v120, v120
	v_exp_f32_e32 v121, v121
	v_exp_f32_e32 v114, v114
	v_exp_f32_e32 v115, v115
	v_exp_f32_e32 v116, v116
	v_exp_f32_e32 v117, v117
	v_pk_fma_f32 v[118:119], v[118:119], v[200:201], v[200:201] op_sel_hi:[1,0,0]
	v_pk_fma_f32 v[120:121], v[120:121], v[200:201], v[200:201] op_sel_hi:[1,0,0]
	v_pk_fma_f32 v[114:115], v[114:115], v[200:201], v[200:201] op_sel_hi:[1,0,0]
	v_pk_fma_f32 v[116:117], v[116:117], v[200:201], v[200:201] op_sel_hi:[1,0,0]
	v_rcp_f32_e32 v118, v118
	v_rcp_f32_e32 v119, v119
	v_rcp_f32_e32 v120, v120
	v_rcp_f32_e32 v121, v121
	v_rcp_f32_e32 v114, v114
	v_rcp_f32_e32 v115, v115
	v_rcp_f32_e32 v116, v116
	v_rcp_f32_e32 v117, v117
	v_pk_mul_f32 v[126:127], v[126:127], v[118:119]
	v_pk_mul_f32 v[128:129], v[128:129], v[120:121]
	v_pk_mul_f32 v[122:123], v[122:123], v[114:115]
	v_pk_mul_f32 v[124:125], v[124:125], v[116:117]
	v_cvt_pk_bf16_f32 v118, v126, v127
	v_cvt_pk_bf16_f32 v119, v128, v129
	v_cvt_pk_bf16_f32 v120, v122, v123
	v_cvt_pk_bf16_f32 v121, v124, v125
	global_store_dwordx4 v161, v[118:121], s[24:25]
	s_cmp_lg_u64 s[8:9], 0
	s_cbranch_scc0 .Lswg_noalign
	s_barrier
.Lswg_noalign:
	v_mul_f32_e32 v228, 0xbfb8aa3b, v163
	v_pk_mul_f32 v[110:111], v[102:103], v[110:111]
	v_pk_mul_f32 v[112:113], v[104:105], v[112:113]
	v_pk_mul_f32 v[106:107], v[98:99], v[106:107]
	v_pk_mul_f32 v[108:109], v[100:101], v[108:109]
	v_pk_mul_f32 v[102:103], v[102:103], v[228:229] op_sel_hi:[1,0]
	v_pk_mul_f32 v[104:105], v[104:105], v[228:229] op_sel_hi:[1,0]
	v_pk_mul_f32 v[98:99], v[98:99], v[228:229] op_sel_hi:[1,0]
	v_pk_mul_f32 v[100:101], v[100:101], v[228:229] op_sel_hi:[1,0]
	v_exp_f32_e32 v102, v102
	v_exp_f32_e32 v103, v103
	v_exp_f32_e32 v104, v104
	v_exp_f32_e32 v105, v105
	v_exp_f32_e32 v98, v98
	v_exp_f32_e32 v99, v99
	v_exp_f32_e32 v100, v100
	v_exp_f32_e32 v101, v101
	v_pk_fma_f32 v[102:103], v[102:103], v[202:203], v[202:203] op_sel_hi:[1,0,0]
	v_pk_fma_f32 v[104:105], v[104:105], v[202:203], v[202:203] op_sel_hi:[1,0,0]
	v_pk_fma_f32 v[98:99], v[98:99], v[202:203], v[202:203] op_sel_hi:[1,0,0]
	v_pk_fma_f32 v[100:101], v[100:101], v[202:203], v[202:203] op_sel_hi:[1,0,0]
	v_rcp_f32_e32 v102, v102
	v_rcp_f32_e32 v103, v103
	v_rcp_f32_e32 v104, v104
	v_rcp_f32_e32 v105, v105
	v_rcp_f32_e32 v98, v98
	v_rcp_f32_e32 v99, v99
	v_rcp_f32_e32 v100, v100
	v_rcp_f32_e32 v101, v101
	v_pk_mul_f32 v[110:111], v[110:111], v[102:103]
	v_pk_mul_f32 v[112:113], v[112:113], v[104:105]
	v_pk_mul_f32 v[106:107], v[106:107], v[98:99]
	v_pk_mul_f32 v[108:109], v[108:109], v[100:101]
	v_cvt_pk_bf16_f32 v102, v110, v111
	v_cvt_pk_bf16_f32 v103, v112, v113
	v_cvt_pk_bf16_f32 v104, v106, v107
	v_cvt_pk_bf16_f32 v105, v108, v109
	v_add_u32_e32 v170, 0x16000, v161
	global_store_dwordx4 v170, v[102:105], s[24:25]
	v_mul_f32_e32 v228, 0xbfb8aa3b, v164
	v_pk_mul_f32 v[94:95], v[86:87], v[94:95]
	v_pk_mul_f32 v[96:97], v[88:89], v[96:97]
	v_pk_mul_f32 v[90:91], v[82:83], v[90:91]
	v_pk_mul_f32 v[92:93], v[84:85], v[92:93]
	v_pk_mul_f32 v[86:87], v[86:87], v[228:229] op_sel_hi:[1,0]
	v_pk_mul_f32 v[88:89], v[88:89], v[228:229] op_sel_hi:[1,0]
	v_pk_mul_f32 v[82:83], v[82:83], v[228:229] op_sel_hi:[1,0]
	v_pk_mul_f32 v[84:85], v[84:85], v[228:229] op_sel_hi:[1,0]
	v_exp_f32_e32 v86, v86
	v_exp_f32_e32 v87, v87
	v_exp_f32_e32 v88, v88
	v_exp_f32_e32 v89, v89
	v_exp_f32_e32 v82, v82
	v_exp_f32_e32 v83, v83
	v_exp_f32_e32 v84, v84
	v_exp_f32_e32 v85, v85
	v_pk_fma_f32 v[86:87], v[86:87], v[204:205], v[204:205] op_sel_hi:[1,0,0]
	v_pk_fma_f32 v[88:89], v[88:89], v[204:205], v[204:205] op_sel_hi:[1,0,0]
	v_pk_fma_f32 v[82:83], v[82:83], v[204:205], v[204:205] op_sel_hi:[1,0,0]
	v_pk_fma_f32 v[84:85], v[84:85], v[204:205], v[204:205] op_sel_hi:[1,0,0]
	v_rcp_f32_e32 v86, v86
	v_rcp_f32_e32 v87, v87
	v_rcp_f32_e32 v88, v88
	v_rcp_f32_e32 v89, v89
	v_rcp_f32_e32 v82, v82
	v_rcp_f32_e32 v83, v83
	v_rcp_f32_e32 v84, v84
	v_rcp_f32_e32 v85, v85
	v_pk_mul_f32 v[94:95], v[94:95], v[86:87]
	v_pk_mul_f32 v[96:97], v[96:97], v[88:89]
	v_pk_mul_f32 v[90:91], v[90:91], v[82:83]
	v_pk_mul_f32 v[92:93], v[92:93], v[84:85]
	v_cvt_pk_bf16_f32 v86, v94, v95
; __device__ __forceinline__ unsigned pk_bf16(float lo, float hi) { f32x2 v = {lo, hi}; bf16x2_t b = __builtin_convertvector(v, bf16x2_t); return __builtin_bit_cast(unsigned, b); }
; __device__ __forceinline__ float fast_exp2(float x) { return __builtin_amdgcn_exp2f(x); }
; __device__ __forceinline__ float fast_rcp(float x) { return __builtin_amdgcn_rcpf(x); }
;     __device__ __forceinline__ void operator()(const f32x4 (&acc)[2][2][4][2], const Unit& u, int wr, int wc, int fr, int fq, float rp0, float rp1, const f32x4& raw0, const f32x4& raw1, float& rn0, float& rn1) const {
;     ...
;         for (int ai = 0; ai < 2; ++ai)
; #pragma unroll
;             for (int m = 0; m < 4; ++m) {
;                 const int row = row0 + ai * HALF + m * 16; const float r = rs[ai * 4 + m];
;                 const float c1 = -1.4426950408889634f * r, r2 = r * r;
;                 const f32x4 ga = acc[ai][0][m][0], gb = acc[ai][0][m][1];
;                 const f32x4 ta = ga * c1, tb = gb * c1;
;                 f32x4 ea, eb;
; #pragma unroll
;                 for (int j = 0; j < 4; ++j) { ea[j] = fast_exp2(ta[j]); eb[j] = fast_exp2(tb[j]); }
;                 const f32x4 da = ea + 1.f, db = eb + 1.f;
;                 f32x4 qa, qb;
; #pragma unroll
;                 for (int j = 0; j < 4; ++j) { qa[j] = fast_rcp(da[j]); qb[j] = fast_rcp(db[j]); }
;                 const f32x4 oa = ((ga * acc[ai][1][m][0]) * r2) * qa, ob = ((gb * acc[ai][1][m][1]) * r2) * qb;
;                 u32x4 w;
;                 w.x = pk_bf16(oa[0], oa[1]); w.y = pk_bf16(oa[2], oa[3]); w.z = pk_bf16(ob[0], ob[1]); w.w = pk_bf16(ob[2], ob[3]);
;                 if (ai == 0 && m == 0) rstd_finish(raw0, raw1, rn0, rn1);
;                 *(u32x4*)(O + (size_t)row * FF + col0) = w;
	v_cvt_pk_bf16_f32 v87, v96, v97
	v_cvt_pk_bf16_f32 v88, v90, v91
	v_cvt_pk_bf16_f32 v89, v92, v93
	v_add_u32_e32 v170, 0x2c000, v161
	global_store_dwordx4 v170, v[86:89], s[24:25]
	v_mul_f32_e32 v228, 0xbfb8aa3b, v165
	v_pk_mul_f32 v[78:79], v[70:71], v[78:79]
	v_pk_mul_f32 v[80:81], v[72:73], v[80:81]
	v_pk_mul_f32 v[74:75], v[62:63], v[74:75]
	v_pk_mul_f32 v[76:77], v[64:65], v[76:77]
	v_pk_mul_f32 v[70:71], v[70:71], v[228:229] op_sel_hi:[1,0]
	v_pk_mul_f32 v[72:73], v[72:73], v[228:229] op_sel_hi:[1,0]
	v_pk_mul_f32 v[62:63], v[62:63], v[228:229] op_sel_hi:[1,0]
	v_pk_mul_f32 v[64:65], v[64:65], v[228:229] op_sel_hi:[1,0]
	v_exp_f32_e32 v70, v70
	v_exp_f32_e32 v71, v71
	v_exp_f32_e32 v72, v72
	v_exp_f32_e32 v73, v73
	v_exp_f32_e32 v62, v62
	v_exp_f32_e32 v63, v63
	v_exp_f32_e32 v64, v64
	v_exp_f32_e32 v65, v65
	v_pk_fma_f32 v[70:71], v[70:71], v[206:207], v[206:207] op_sel_hi:[1,0,0]
	v_pk_fma_f32 v[72:73], v[72:73], v[206:207], v[206:207] op_sel_hi:[1,0,0]
	v_pk_fma_f32 v[62:63], v[62:63], v[206:207], v[206:207] op_sel_hi:[1,0,0]
	v_pk_fma_f32 v[64:65], v[64:65], v[206:207], v[206:207] op_sel_hi:[1,0,0]
	v_rcp_f32_e32 v70, v70
	v_rcp_f32_e32 v71, v71
	v_rcp_f32_e32 v72, v72
	v_rcp_f32_e32 v73, v73
	v_rcp_f32_e32 v62, v62
	v_rcp_f32_e32 v63, v63
	v_rcp_f32_e32 v64, v64
	v_rcp_f32_e32 v65, v65
	v_pk_mul_f32 v[78:79], v[78:79], v[70:71]
	v_pk_mul_f32 v[80:81], v[80:81], v[72:73]
	v_pk_mul_f32 v[74:75], v[74:75], v[62:63]
	v_pk_mul_f32 v[76:77], v[76:77], v[64:65]
	v_cvt_pk_bf16_f32 v70, v78, v79
	v_cvt_pk_bf16_f32 v71, v80, v81
	v_cvt_pk_bf16_f32 v72, v74, v75
	v_cvt_pk_bf16_f32 v73, v76, v77
	v_add_u32_e32 v170, 0x42000, v161
	global_store_dwordx4 v170, v[70:73], s[24:25]
	v_mul_f32_e32 v228, 0xbfb8aa3b, v166
	v_pk_mul_f32 v[66:67], v[54:55], v[66:67]
	v_pk_mul_f32 v[68:69], v[56:57], v[68:69]
	v_pk_mul_f32 v[58:59], v[50:51], v[58:59]
	v_pk_mul_f32 v[60:61], v[52:53], v[60:61]
	v_pk_mul_f32 v[54:55], v[54:55], v[228:229] op_sel_hi:[1,0]
	v_pk_mul_f32 v[56:57], v[56:57], v[228:229] op_sel_hi:[1,0]
	v_pk_mul_f32 v[50:51], v[50:51], v[228:229] op_sel_hi:[1,0]
	v_pk_mul_f32 v[52:53], v[52:53], v[228:229] op_sel_hi:[1,0]
	v_exp_f32_e32 v54, v54
	v_exp_f32_e32 v55, v55
	v_exp_f32_e32 v56, v56
	v_exp_f32_e32 v57, v57
	v_exp_f32_e32 v50, v50
	v_exp_f32_e32 v51, v51
	v_exp_f32_e32 v52, v52
	v_exp_f32_e32 v53, v53
	v_pk_fma_f32 v[54:55], v[54:55], v[220:221], v[220:221] op_sel_hi:[1,0,0]
	v_pk_fma_f32 v[56:57], v[56:57], v[220:221], v[220:221] op_sel_hi:[1,0,0]
	v_pk_fma_f32 v[50:51], v[50:51], v[220:221], v[220:221] op_sel_hi:[1,0,0]
	v_pk_fma_f32 v[52:53], v[52:53], v[220:221], v[220:221] op_sel_hi:[1,0,0]
	v_rcp_f32_e32 v54, v54
	v_rcp_f32_e32 v55, v55
	v_rcp_f32_e32 v56, v56
	v_rcp_f32_e32 v57, v57
	v_rcp_f32_e32 v50, v50
	v_rcp_f32_e32 v51, v51
	v_rcp_f32_e32 v52, v52
	v_rcp_f32_e32 v53, v53
	v_pk_mul_f32 v[66:67], v[66:67], v[54:55]
	v_pk_mul_f32 v[68:69], v[68:69], v[56:57]
	v_pk_mul_f32 v[58:59], v[58:59], v[50:51]
	v_pk_mul_f32 v[60:61], v[60:61], v[52:53]
	v_cvt_pk_bf16_f32 v54, v66, v67
	v_cvt_pk_bf16_f32 v55, v68, v69
	v_cvt_pk_bf16_f32 v56, v58, v59
	v_cvt_pk_bf16_f32 v57, v60, v61
	v_add_u32_e32 v170, 0xb0000, v161
	global_store_dwordx4 v170, v[54:57], s[24:25]
	v_mul_f32_e32 v228, 0xbfb8aa3b, v167
	v_pk_mul_f32 v[46:47], v[38:39], v[46:47]
	v_pk_mul_f32 v[48:49], v[40:41], v[48:49]
	v_pk_mul_f32 v[42:43], v[34:35], v[42:43]
	v_pk_mul_f32 v[44:45], v[36:37], v[44:45]
	v_pk_mul_f32 v[38:39], v[38:39], v[228:229] op_sel_hi:[1,0]
	v_pk_mul_f32 v[40:41], v[40:41], v[228:229] op_sel_hi:[1,0]
	v_pk_mul_f32 v[34:35], v[34:35], v[228:229] op_sel_hi:[1,0]
	v_pk_mul_f32 v[36:37], v[36:37], v[228:229] op_sel_hi:[1,0]
	v_exp_f32_e32 v38, v38
	v_exp_f32_e32 v39, v39
	v_exp_f32_e32 v40, v40
	v_exp_f32_e32 v41, v41
	v_exp_f32_e32 v34, v34
	v_exp_f32_e32 v35, v35
	v_exp_f32_e32 v36, v36
	v_exp_f32_e32 v37, v37
	v_pk_fma_f32 v[38:39], v[38:39], v[222:223], v[222:223] op_sel_hi:[1,0,0]
	v_pk_fma_f32 v[40:41], v[40:41], v[222:223], v[222:223] op_sel_hi:[1,0,0]
	v_pk_fma_f32 v[34:35], v[34:35], v[222:223], v[222:223] op_sel_hi:[1,0,0]
	v_pk_fma_f32 v[36:37], v[36:37], v[222:223], v[222:223] op_sel_hi:[1,0,0]
	v_rcp_f32_e32 v38, v38
	v_rcp_f32_e32 v39, v39
	v_rcp_f32_e32 v40, v40
	v_rcp_f32_e32 v41, v41
	v_rcp_f32_e32 v34, v34
	v_rcp_f32_e32 v35, v35
	v_rcp_f32_e32 v36, v36
	v_rcp_f32_e32 v37, v37
	v_pk_mul_f32 v[46:47], v[46:47], v[38:39]
; __device__ __forceinline__ unsigned pk_bf16(float lo, float hi) { f32x2 v = {lo, hi}; bf16x2_t b = __builtin_convertvector(v, bf16x2_t); return __builtin_bit_cast(unsigned, b); }
; __device__ __forceinline__ float fast_exp2(float x) { return __builtin_amdgcn_exp2f(x); }
; __device__ __forceinline__ float fast_rcp(float x) { return __builtin_amdgcn_rcpf(x); }
; __device__ __forceinline__ void rstd_finish(const f32x4& raw0, const f32x4& raw1, float& rn0, float& rn1) {
;     rn0 = rsqrtf(((raw0.x + raw0.y) + (raw0.z + raw0.w)) * (1.f / DM) + EPS); rn1 = rsqrtf(((raw1.x + raw1.y) + (raw1.z + raw1.w)) * (1.f / DM) + EPS);
;     asm volatile("" :: "v"(rn0), "v"(rn1) : "memory");
; }
;     __device__ __forceinline__ void operator()(const f32x4 (&acc)[2][2][4][2], const Unit& u, int wr, int wc, int fr, int fq, float rp0, float rp1, const f32x4& raw0, const f32x4& raw1, float& rn0, float& rn1) const {
;     ...
;                 const int row = row0 + ai * HALF + m * 16; const float r = rs[ai * 4 + m];
;                 const float c1 = -1.4426950408889634f * r, r2 = r * r;
;                 const f32x4 ga = acc[ai][0][m][0], gb = acc[ai][0][m][1];
;                 const f32x4 ta = ga * c1, tb = gb * c1;
;                 f32x4 ea, eb;
; #pragma unroll
;                 for (int j = 0; j < 4; ++j) { ea[j] = fast_exp2(ta[j]); eb[j] = fast_exp2(tb[j]); }
;                 const f32x4 da = ea + 1.f, db = eb + 1.f;
;                 f32x4 qa, qb;
; #pragma unroll
;                 for (int j = 0; j < 4; ++j) { qa[j] = fast_rcp(da[j]); qb[j] = fast_rcp(db[j]); }
;                 const f32x4 oa = ((ga * acc[ai][1][m][0]) * r2) * qa, ob = ((gb * acc[ai][1][m][1]) * r2) * qb;
;                 u32x4 w;
;                 w.x = pk_bf16(oa[0], oa[1]); w.y = pk_bf16(oa[2], oa[3]); w.z = pk_bf16(ob[0], ob[1]); w.w = pk_bf16(ob[2], ob[3]);
;                 if (ai == 0 && m == 0) rstd_finish(raw0, raw1, rn0, rn1);
;                 *(u32x4*)(O + (size_t)row * FF + col0) = w;
	v_pk_mul_f32 v[48:49], v[48:49], v[40:41]
	v_pk_mul_f32 v[42:43], v[42:43], v[34:35]
	v_pk_mul_f32 v[44:45], v[44:45], v[36:37]
	v_cvt_pk_bf16_f32 v38, v46, v47
	v_cvt_pk_bf16_f32 v39, v48, v49
	v_cvt_pk_bf16_f32 v40, v42, v43
	v_cvt_pk_bf16_f32 v41, v44, v45
	v_add_u32_e32 v170, 0xc6000, v161
	global_store_dwordx4 v170, v[38:41], s[24:25]
	v_mul_f32_e32 v228, 0xbfb8aa3b, v168
	v_pk_mul_f32 v[30:31], v[22:23], v[30:31]
	v_pk_mul_f32 v[32:33], v[24:25], v[32:33]
	v_pk_mul_f32 v[26:27], v[18:19], v[26:27]
	v_pk_mul_f32 v[28:29], v[20:21], v[28:29]
	v_pk_mul_f32 v[22:23], v[22:23], v[228:229] op_sel_hi:[1,0]
	v_pk_mul_f32 v[24:25], v[24:25], v[228:229] op_sel_hi:[1,0]
	v_pk_mul_f32 v[18:19], v[18:19], v[228:229] op_sel_hi:[1,0]
	v_pk_mul_f32 v[20:21], v[20:21], v[228:229] op_sel_hi:[1,0]
	v_exp_f32_e32 v22, v22
	v_exp_f32_e32 v23, v23
	v_exp_f32_e32 v24, v24
	v_exp_f32_e32 v25, v25
	v_exp_f32_e32 v18, v18
	v_exp_f32_e32 v19, v19
	v_exp_f32_e32 v20, v20
	v_exp_f32_e32 v21, v21
	v_pk_fma_f32 v[22:23], v[22:23], v[224:225], v[224:225] op_sel_hi:[1,0,0]
	v_pk_fma_f32 v[24:25], v[24:25], v[224:225], v[224:225] op_sel_hi:[1,0,0]
	v_pk_fma_f32 v[18:19], v[18:19], v[224:225], v[224:225] op_sel_hi:[1,0,0]
	v_pk_fma_f32 v[20:21], v[20:21], v[224:225], v[224:225] op_sel_hi:[1,0,0]
	v_rcp_f32_e32 v22, v22
	v_rcp_f32_e32 v23, v23
	v_rcp_f32_e32 v24, v24
	v_rcp_f32_e32 v25, v25
	v_rcp_f32_e32 v18, v18
	v_rcp_f32_e32 v19, v19
	v_rcp_f32_e32 v20, v20
	v_rcp_f32_e32 v21, v21
	v_pk_mul_f32 v[30:31], v[30:31], v[22:23]
	v_pk_mul_f32 v[32:33], v[32:33], v[24:25]
	v_pk_mul_f32 v[26:27], v[26:27], v[18:19]
	v_pk_mul_f32 v[28:29], v[28:29], v[20:21]
	v_cvt_pk_bf16_f32 v22, v30, v31
	v_cvt_pk_bf16_f32 v23, v32, v33
	v_cvt_pk_bf16_f32 v24, v26, v27
	v_cvt_pk_bf16_f32 v25, v28, v29
	v_add_u32_e32 v170, 0xdc000, v161
	global_store_dwordx4 v170, v[22:25], s[24:25]
	v_mul_f32_e32 v228, 0xbfb8aa3b, v169
	v_pk_mul_f32 v[14:15], v[6:7], v[14:15]
	v_pk_mul_f32 v[16:17], v[8:9], v[16:17]
	v_pk_mul_f32 v[10:11], v[2:3], v[10:11]
	v_pk_mul_f32 v[12:13], v[4:5], v[12:13]
	v_pk_mul_f32 v[6:7], v[6:7], v[228:229] op_sel_hi:[1,0]
	v_pk_mul_f32 v[8:9], v[8:9], v[228:229] op_sel_hi:[1,0]
	v_pk_mul_f32 v[2:3], v[2:3], v[228:229] op_sel_hi:[1,0]
	v_pk_mul_f32 v[4:5], v[4:5], v[228:229] op_sel_hi:[1,0]
	v_exp_f32_e32 v6, v6
	v_exp_f32_e32 v7, v7
	v_exp_f32_e32 v8, v8
	v_exp_f32_e32 v9, v9
	v_exp_f32_e32 v2, v2
	v_exp_f32_e32 v3, v3
	v_exp_f32_e32 v4, v4
	v_exp_f32_e32 v5, v5
	v_pk_fma_f32 v[6:7], v[6:7], v[226:227], v[226:227] op_sel_hi:[1,0,0]
	v_pk_fma_f32 v[8:9], v[8:9], v[226:227], v[226:227] op_sel_hi:[1,0,0]
	v_pk_fma_f32 v[2:3], v[2:3], v[226:227], v[226:227] op_sel_hi:[1,0,0]
	v_pk_fma_f32 v[4:5], v[4:5], v[226:227], v[226:227] op_sel_hi:[1,0,0]
	v_rcp_f32_e32 v6, v6
	v_rcp_f32_e32 v7, v7
	v_rcp_f32_e32 v8, v8
	v_rcp_f32_e32 v9, v9
	v_rcp_f32_e32 v2, v2
	v_rcp_f32_e32 v3, v3
	v_rcp_f32_e32 v4, v4
	v_rcp_f32_e32 v5, v5
	v_pk_mul_f32 v[14:15], v[14:15], v[6:7]
	v_pk_mul_f32 v[16:17], v[16:17], v[8:9]
	v_pk_mul_f32 v[10:11], v[10:11], v[2:3]
	v_pk_mul_f32 v[12:13], v[12:13], v[4:5]
	v_cvt_pk_bf16_f32 v6, v14, v15
	v_cvt_pk_bf16_f32 v7, v16, v17
	v_cvt_pk_bf16_f32 v8, v10, v11
	v_cvt_pk_bf16_f32 v9, v12, v13
	v_add_u32_e32 v170, 0xf2000, v161
	global_store_dwordx4 v170, v[6:9], s[24:25]
	s_waitcnt vmcnt(8)
	v_mov_b32_e32 v122, v135
	v_mov_b32_e32 v123, v136
	v_mov_b32_e32 v135, v137
	v_mov_b32_e32 v124, v131
	v_mov_b32_e32 v125, v132
	v_mov_b32_e32 v131, v133
	v_pk_add_f32 v[122:123], v[122:123], v[134:135]
	v_pk_add_f32 v[124:125], v[124:125], v[130:131]
	v_mov_b32_e32 v126, v124
	v_mov_b32_e32 v127, v122
	v_mov_b32_e32 v122, v125
	v_pk_add_f32 v[122:123], v[126:127], v[122:123]
	v_pk_fma_f32 v[122:123], v[122:123], s[84:85], v[182:183] op_sel_hi:[1,0,0]
	v_mov_b32_e32 v252, v122
	v_mov_b32_e32 v253, v123
	v_mul_f32_e32 v119, 0x4b800000, v123
	v_mul_f32_e32 v118, 0x4b800000, v122
	v_cmp_gt_f32_e64 s[100:101], s89, v123
	v_cmp_gt_f32_e64 s[6:7], s89, v122
	s_nop 1
	v_cndmask_b32_e64 v119, v123, v119, s[100:101]
	v_cndmask_b32_e64 v118, v122, v118, s[6:7]
	v_rsq_f32_e32 v123, v119
	v_rsq_f32_e32 v122, v118
	s_nop 0
	v_pk_mul_f32 v[120:121], v[122:123], s[78:79] op_sel_hi:[1,0]
	v_cndmask_b32_e64 v145, v123, v121, s[100:101]
	v_cndmask_b32_e64 v144, v122, v120, s[6:7]
	s_cbranch_vccnz .LBB0_315
	s_andn2_b64 vcc, exec, s[2:3]
	s_cbranch_vccnz .LBB0_314
	s_barrier
	s_branch .LBB0_314
